# early L1 invalidate in grid barriers + accumulator zeroing with v_mov_b64 (half the instructions per tile)
# baseline (speedup 1.0000x reference)
; #define PG8_STAGE(bufoff, gbase, voff) do { _Pragma("unroll") for (int _i = 0; _i < 2; ++_i) \
;         __builtin_amdgcn_global_load_lds((const unsigned*)((const char*)(gbase) + (voff)[_i]), (LAS unsigned*)(lds + (bufoff) + ldsw + _i * 8192), 16, 0, 0); } while (0)
; #define PG8_WAIT_V(n) asm volatile("s_waitcnt vmcnt(" #n ")" ::: "memory")
; #define PG8_BAR __builtin_amdgcn_s_barrier()
; #define PG8_WAIT_V(n) asm volatile("s_waitcnt vmcnt(" #n ")" ::: "memory")
; #define PG8_BAR __builtin_amdgcn_s_barrier()
; template <class Epi, class Sched>
; DI void gemm_phase(LAS unsigned char* lds, const Gemm g, const Sched& S, const Epi& E) {
;     ...
;     f32x4 acc[2][2][4][2];
; #pragma unroll
;     for (int a = 0; a < 2; ++a)
; #pragma unroll
;         for (int b = 0; b < 2; ++b)
; #pragma unroll
;             for (int m = 0; m < 4; ++m)
; #pragma unroll
;                 for (int n = 0; n < 2; ++n) acc[a][b][m][n] = (f32x4){0.f, 0.f, 0.f, 0.f};
;     ...
;     PG8_STAGE(PG8_SB(0, 0), cB, voffB); PG8_STAGE(PG8_SB(0, 1), cB + hstepB, voffB); PG8_STAGE(PG8_SA(0, 0), cA, voffA); PG8_STAGE(PG8_SA(0, 1), cA + hstepA, voffA);
;     if (wr == 1) PG8_BAR;
;     PG8_WAIT_V(2); PG8_BAR;
;     PG8_STAGE(PG8_SB(1, 0), cB + kstep, voffB); PG8_STAGE(PG8_SA(1, 0), cA + kstep, voffA); PG8_STAGE(PG8_SB(1, 1), cB + hstepB + kstep, voffB);
;     PG8_WAIT_V(6); PG8_BAR;
.LBB0_203:
	v_and_b32_e32 v198, 15, v0
	v_bfe_u32 v16, v0, 4, 2
	s_and_b32 s12, s12, 3
	v_lshlrev_b32_e32 v0, 4, v16
	v_lshlrev_b32_e32 v18, 2, v198
	v_lshl_or_b32 v17, v198, 6, v0
	s_lshl_b32 s13, s15, 13
	v_and_b32_e32 v19, 32, v18
	s_lshl_b32 s91, s12, 5
	s_lshl_b32 s12, s12, 12
	s_add_i32 m0, s52, 0x18000
	v_lshl_add_u64 v[8:9], v[8:9], 0, s[26:27]
	s_lshl_b32 s90, s15, 6
	v_bitop3_b32 v20, v17, s13, v19 bitop3:0xde
	v_bitop3_b32 v200, v17, s12, v19 bitop3:0xde
	s_waitcnt vmcnt(2)
	s_barrier
	global_load_lds_dwordx4 v[8:9], off
	v_lshl_add_u64 v[6:7], v[6:7], 0, s[26:27]
	s_add_i32 m0, s52, 0x1a000
	s_add_i32 s12, s52, 0x8000
	s_add_i32 s13, s52, 0xa000
	global_load_lds_dwordx4 v[6:7], off
	v_lshl_add_u64 v[4:5], v[4:5], 0, s[26:27]
	s_mov_b32 m0, s12
	s_add_u32 s16, s36, 0x40080
	global_load_lds_dwordx4 v[4:5], off
	v_lshl_add_u64 v[2:3], v[2:3], 0, s[26:27]
	s_mov_b32 m0, s13
	s_addc_u32 s17, s37, 0
	global_load_lds_dwordx4 v[2:3], off
	s_add_i32 m0, s52, 0x1c000
	v_lshl_add_u64 v[2:3], s[16:17], 0, v[164:165]
	global_load_lds_dwordx4 v[2:3], off
	v_lshl_add_u64 v[2:3], s[16:17], 0, v[168:169]
	s_add_i32 m0, s52, 0x1e000
	v_and_b32_e32 v0, 16, v0
	global_load_lds_dwordx4 v[2:3], off
	v_lshl_add_u64 v[2:3], s[62:63], 0, v[0:1]
	s_mov_b64 s[16:17], 0x17a00000
	v_lshlrev_b32_e32 v0, 5, v16
	v_lshl_add_u64 v[170:171], v[2:3], 0, s[16:17]
	v_lshl_add_u64 v[2:3], s[30:31], 0, v[0:1]
	v_lshlrev_b32_e32 v0, 5, v198
	v_lshl_add_u64 v[174:175], v[170:171], 0, v[0:1]
	v_lshlrev_b32_e32 v0, 14, v10
	s_mov_b64 s[16:17], 0x100000
	v_and_b32_e32 v0, 0xffff8000, v0
	v_lshl_add_u64 v[172:173], v[2:3], 0, s[16:17]
	v_lshl_add_u32 v0, v11, 11, v0
	v_and_b32_e32 v2, 1, v10
	s_lshl_b32 s15, s15, 8
	v_lshl_or_b32 v0, v2, 6, v0
	s_add_i32 s15, s15, 0
	v_lshl_add_u32 v176, v12, 1, v0
	v_lshlrev_b32_e32 v0, 14, v13
	s_add_i32 s15, s15, 0x20000
	v_and_b32_e32 v0, 0xffff8000, v0
	s_waitcnt vmcnt(6)
	s_cmpk_lt_u32 s14, 0x100
	v_lshl_add_u32 v0, v14, 11, v0
	v_and_b32_e32 v2, 1, v13
	s_cselect_b64 s[70:71], -1, 0
	s_bitcmp0_b32 s14, 6
	v_lshlrev_b32_e32 v4, 2, v16
	v_lshl_or_b32 v0, v2, 6, v0
	v_lshlrev_b32_e32 v199, 3, v16
	v_add_u32_e32 v201, s15, v18
	s_mov_b32 s14, 0
	s_cselect_b64 s[72:73], -1, 0
	v_cmp_gt_u32_e64 s[84:85], 2, v16
	v_mov_b32_e32 v177, v1
	v_lshl_add_u32 v178, v15, 1, v0
	v_mov_b32_e32 v179, v1
	v_add_u32_e32 v208, 0, v20
	v_lshlrev_b32_e32 v0, 1, v4
	v_mov_b64_e32 v[2:3], 0
	v_mov_b64_e32 v[4:5], 0
	v_mov_b64_e32 v[6:7], 0
	v_mov_b64_e32 v[8:9], 0
	v_mov_b64_e32 v[10:11], 0
	v_mov_b64_e32 v[12:13], 0
	v_mov_b64_e32 v[14:15], 0
	v_mov_b64_e32 v[16:17], 0
	v_mov_b64_e32 v[18:19], 0
	v_mov_b64_e32 v[20:21], 0
	v_mov_b64_e32 v[22:23], 0
	v_mov_b64_e32 v[24:25], 0
	v_mov_b64_e32 v[26:27], 0
	v_mov_b64_e32 v[28:29], 0
	v_mov_b64_e32 v[30:31], 0
	v_mov_b64_e32 v[32:33], 0
	v_mov_b64_e32 v[34:35], 0
	v_mov_b64_e32 v[36:37], 0
	v_mov_b64_e32 v[38:39], 0
	v_mov_b64_e32 v[40:41], 0
	v_mov_b64_e32 v[42:43], 0
	v_mov_b64_e32 v[44:45], 0
	v_mov_b64_e32 v[46:47], 0
	v_mov_b64_e32 v[48:49], 0
	v_mov_b64_e32 v[50:51], 0
	v_mov_b64_e32 v[52:53], 0
	v_mov_b64_e32 v[54:55], 0
	v_mov_b64_e32 v[56:57], 0
	v_mov_b64_e32 v[58:59], 0
	v_mov_b64_e32 v[60:61], 0
	v_mov_b64_e32 v[62:63], 0
	v_mov_b64_e32 v[64:65], 0
	v_mov_b64_e32 v[66:67], 0
	v_mov_b64_e32 v[68:69], 0
	v_mov_b64_e32 v[70:71], 0
	v_mov_b64_e32 v[72:73], 0
	v_mov_b64_e32 v[74:75], 0
	v_mov_b64_e32 v[76:77], 0
	v_mov_b64_e32 v[78:79], 0
	v_mov_b64_e32 v[80:81], 0
	v_mov_b64_e32 v[82:83], 0
	v_mov_b64_e32 v[84:85], 0
	v_mov_b64_e32 v[86:87], 0
	v_mov_b64_e32 v[88:89], 0
	v_mov_b64_e32 v[90:91], 0
	v_mov_b64_e32 v[92:93], 0
	v_mov_b64_e32 v[94:95], 0
	v_mov_b64_e32 v[96:97], 0
	v_mov_b64_e32 v[98:99], 0
	v_mov_b64_e32 v[100:101], 0
	v_mov_b64_e32 v[102:103], 0
	v_mov_b64_e32 v[104:105], 0
	v_mov_b64_e32 v[106:107], 0
	v_mov_b64_e32 v[108:109], 0
	v_mov_b64_e32 v[110:111], 0
	v_mov_b64_e32 v[112:113], 0
	v_mov_b64_e32 v[114:115], 0
	v_mov_b64_e32 v[116:117], 0
	v_mov_b64_e32 v[118:119], 0
	v_mov_b64_e32 v[120:121], 0
	v_mov_b64_e32 v[122:123], 0
	v_mov_b64_e32 v[124:125], 0
	v_mov_b64_e32 v[126:127], 0
	v_mov_b64_e32 v[128:129], 0
	s_barrier
	s_branch .LBB0_205
.LBB0_204:
	s_mov_b32 s64, s78
	s_mov_b32 s66, s76
	v_mov_b64_e32 v[2:3], 0
	v_mov_b64_e32 v[4:5], 0
	v_mov_b64_e32 v[6:7], 0
	v_mov_b64_e32 v[8:9], 0
	v_mov_b64_e32 v[10:11], 0
	v_mov_b64_e32 v[12:13], 0
	v_mov_b64_e32 v[14:15], 0
	v_mov_b64_e32 v[16:17], 0
	v_mov_b64_e32 v[18:19], 0
	v_mov_b64_e32 v[20:21], 0
	v_mov_b64_e32 v[22:23], 0
	v_mov_b64_e32 v[24:25], 0
	v_mov_b64_e32 v[26:27], 0
	v_mov_b64_e32 v[28:29], 0
	v_mov_b64_e32 v[30:31], 0
	v_mov_b64_e32 v[32:33], 0
	v_mov_b64_e32 v[34:35], 0
	v_mov_b64_e32 v[36:37], 0
	v_mov_b64_e32 v[38:39], 0
	v_mov_b64_e32 v[40:41], 0
	v_mov_b64_e32 v[42:43], 0
	v_mov_b64_e32 v[44:45], 0
	v_mov_b64_e32 v[46:47], 0
	v_mov_b64_e32 v[48:49], 0
	v_mov_b64_e32 v[50:51], 0
	v_mov_b64_e32 v[52:53], 0
	v_mov_b64_e32 v[54:55], 0
	v_mov_b64_e32 v[56:57], 0
	v_mov_b64_e32 v[58:59], 0
	v_mov_b64_e32 v[60:61], 0
	v_mov_b64_e32 v[62:63], 0
	v_mov_b64_e32 v[64:65], 0
	v_mov_b64_e32 v[66:67], 0
	v_mov_b64_e32 v[68:69], 0
	v_mov_b64_e32 v[70:71], 0
	v_mov_b64_e32 v[72:73], 0
	v_mov_b64_e32 v[74:75], 0
	v_mov_b64_e32 v[76:77], 0
	v_mov_b64_e32 v[78:79], 0
	v_mov_b64_e32 v[80:81], 0
	v_mov_b64_e32 v[82:83], 0
	v_mov_b64_e32 v[84:85], 0
	v_mov_b64_e32 v[86:87], 0
	v_mov_b64_e32 v[88:89], 0
	v_mov_b64_e32 v[90:91], 0
	v_mov_b64_e32 v[92:93], 0
	v_mov_b64_e32 v[94:95], 0
	v_mov_b64_e32 v[96:97], 0
	v_mov_b64_e32 v[98:99], 0
	v_mov_b64_e32 v[100:101], 0
	v_mov_b64_e32 v[102:103], 0
	v_mov_b64_e32 v[104:105], 0
	v_mov_b64_e32 v[106:107], 0
	v_mov_b64_e32 v[108:109], 0
	v_mov_b64_e32 v[110:111], 0
	v_mov_b64_e32 v[112:113], 0
	v_mov_b64_e32 v[114:115], 0
	v_mov_b64_e32 v[116:117], 0
	v_mov_b64_e32 v[118:119], 0
	v_mov_b64_e32 v[120:121], 0
	v_mov_b64_e32 v[122:123], 0
	v_mov_b64_e32 v[124:125], 0
	v_mov_b64_e32 v[126:127], 0
	v_mov_b64_e32 v[128:129], 0
	s_mov_b64 s[74:75], s[82:83]
	s_mov_b32 s14, s15
	s_andn2_b64 vcc, exec, s[92:93]
	s_mov_b64 s[36:37], s[80:81]
	s_cbranch_vccz .LBB0_360

; template <class Epi, class Sched>
; DI void gemm_phase(LAS unsigned char* lds, const Gemm g, const Sched& S, const Epi& E) {
;     ...
;         const char* nA = has_next ? (const char*)g.A + (size_t)nxt.z * g.zA * 2 + (size_t)nxt.pm * 2 * hstepA : cA;
;         const char* nB = has_next ? (const char*)g.Bt + (size_t)nxt.z * g.zB * 2 + (size_t)nxt.pn * 2 * hstepB : cB;
;     ...
; #pragma unroll
;         for (int a = 0; a < 2; ++a)
; #pragma unroll
;             for (int b = 0; b < 2; ++b)
; #pragma unroll
;                 for (int m = 0; m < 4; ++m)
; #pragma unroll
;                     for (int n = 0; n < 2; ++n) acc[a][b][m][n] = (f32x4){0.f, 0.f, 0.f, 0.f};
.LBB0_370:
	s_ashr_i32 s45, s44, 31
	s_lshl_b64 s[40:41], s[44:45], 22
	s_add_u32 s63, s12, s40
	s_addc_u32 s67, s13, s41
	s_ashr_i32 s51, s50, 31
	s_lshl_b64 s[40:41], s[50:51], 19
	s_add_u32 s66, s63, s40
	s_addc_u32 s67, s67, s41
	s_and_b64 s[40:41], s[64:65], exec
	s_cselect_b32 s40, s67, s39
	s_cselect_b32 s41, s66, s38
	s_lshl_b64 s[68:69], s[44:45], 21
	s_add_u32 s45, s14, s68
	s_addc_u32 s51, s15, s69
	s_ashr_i32 s63, s62, 31
	s_lshl_b64 s[68:69], s[62:63], 19
	s_add_u32 s68, s45, s68
	s_addc_u32 s69, s51, s69
	s_and_b64 s[70:71], s[64:65], exec
	s_cselect_b32 s45, s69, s37
	s_cselect_b32 s51, s68, s36
	s_add_u32 s70, s38, 0x40080
	s_addc_u32 s71, s39, 0
	s_add_u32 s63, s36, 0x100
	s_addc_u32 s81, s37, 0
	s_mov_b32 s82, -2
	v_mov_b64_e32 v[2:3], 0
	v_mov_b64_e32 v[4:5], 0
	v_mov_b64_e32 v[6:7], 0
	v_mov_b64_e32 v[8:9], 0
	v_mov_b64_e32 v[10:11], 0
	v_mov_b64_e32 v[12:13], 0
	v_mov_b64_e32 v[14:15], 0
	v_mov_b64_e32 v[16:17], 0
	v_mov_b64_e32 v[18:19], 0
	v_mov_b64_e32 v[20:21], 0
	v_mov_b64_e32 v[22:23], 0
	v_mov_b64_e32 v[24:25], 0
	v_mov_b64_e32 v[26:27], 0
	v_mov_b64_e32 v[28:29], 0
	v_mov_b64_e32 v[30:31], 0
	v_mov_b64_e32 v[32:33], 0
	v_mov_b64_e32 v[34:35], 0
	v_mov_b64_e32 v[36:37], 0
	v_mov_b64_e32 v[38:39], 0
	v_mov_b64_e32 v[40:41], 0
	v_mov_b64_e32 v[42:43], 0
	v_mov_b64_e32 v[44:45], 0
	v_mov_b64_e32 v[46:47], 0
	v_mov_b64_e32 v[48:49], 0
	v_mov_b64_e32 v[50:51], 0
	v_mov_b64_e32 v[52:53], 0
	v_mov_b64_e32 v[54:55], 0
	v_mov_b64_e32 v[56:57], 0
	v_mov_b64_e32 v[58:59], 0
	v_mov_b64_e32 v[60:61], 0
	v_mov_b64_e32 v[62:63], 0
	v_mov_b64_e32 v[64:65], 0
	v_mov_b64_e32 v[66:67], 0
	v_mov_b64_e32 v[68:69], 0
	v_mov_b64_e32 v[70:71], 0
	v_mov_b64_e32 v[72:73], 0
	v_mov_b64_e32 v[74:75], 0
	v_mov_b64_e32 v[76:77], 0
	v_mov_b64_e32 v[78:79], 0
	v_mov_b64_e32 v[80:81], 0
	v_mov_b64_e32 v[82:83], 0
	v_mov_b64_e32 v[84:85], 0
	v_mov_b64_e32 v[86:87], 0
	v_mov_b64_e32 v[88:89], 0
	v_mov_b64_e32 v[90:91], 0
	v_mov_b64_e32 v[92:93], 0
	v_mov_b64_e32 v[94:95], 0
	v_mov_b64_e32 v[96:97], 0
	v_mov_b64_e32 v[98:99], 0
	v_mov_b64_e32 v[100:101], 0
	v_mov_b64_e32 v[102:103], 0
	v_mov_b64_e32 v[104:105], 0
	v_mov_b64_e32 v[106:107], 0
	v_mov_b64_e32 v[108:109], 0
	v_mov_b64_e32 v[110:111], 0
	v_mov_b64_e32 v[112:113], 0
	v_mov_b64_e32 v[114:115], 0
	v_mov_b64_e32 v[116:117], 0
	v_mov_b64_e32 v[118:119], 0
	v_mov_b64_e32 v[120:121], 0
	v_mov_b64_e32 v[122:123], 0
	v_mov_b64_e32 v[124:125], 0
	v_mov_b64_e32 v[126:127], 0
	v_mov_b64_e32 v[128:129], 0

; template <class Epi, class Sched>
; DI void gemm_phase(LAS unsigned char* lds, const Gemm g, const Sched& S, const Epi& E) {
;     ...
;         const char* nA = has_next ? (const char*)g.A + (size_t)nxt.z * g.zA * 2 + (size_t)nxt.pm * 2 * hstepA : cA;
;         const char* nB = has_next ? (const char*)g.Bt + (size_t)nxt.z * g.zB * 2 + (size_t)nxt.pn * 2 * hstepB : cB;
;     ...
; #pragma unroll
;         for (int a = 0; a < 2; ++a)
; #pragma unroll
;             for (int b = 0; b < 2; ++b)
; #pragma unroll
;                 for (int m = 0; m < 4; ++m)
; #pragma unroll
;                     for (int n = 0; n < 2; ++n) acc[a][b][m][n] = (f32x4){0.f, 0.f, 0.f, 0.f};
.LBB0_440:
	s_lshl_b64 s[40:41], s[50:51], 18
	s_add_u32 s52, s14, s40
	s_addc_u32 s53, s15, s41
	s_and_b64 s[40:41], s[68:69], exec
	s_cselect_b32 s51, s53, s39
	s_cselect_b32 s68, s52, s38
	s_add_u32 s69, s38, 0x100
	s_addc_u32 s79, s39, 0
	s_mov_b32 s80, -2
	v_mov_b64_e32 v[2:3], 0
	v_mov_b64_e32 v[4:5], 0
	v_mov_b64_e32 v[6:7], 0
	v_mov_b64_e32 v[8:9], 0
	v_mov_b64_e32 v[10:11], 0
	v_mov_b64_e32 v[12:13], 0
	v_mov_b64_e32 v[14:15], 0
	v_mov_b64_e32 v[16:17], 0
	v_mov_b64_e32 v[18:19], 0
	v_mov_b64_e32 v[20:21], 0
	v_mov_b64_e32 v[22:23], 0
	v_mov_b64_e32 v[24:25], 0
	v_mov_b64_e32 v[26:27], 0
	v_mov_b64_e32 v[28:29], 0
	v_mov_b64_e32 v[30:31], 0
	v_mov_b64_e32 v[32:33], 0
	v_mov_b64_e32 v[34:35], 0
	v_mov_b64_e32 v[36:37], 0
	v_mov_b64_e32 v[38:39], 0
	v_mov_b64_e32 v[40:41], 0
	v_mov_b64_e32 v[42:43], 0
	v_mov_b64_e32 v[44:45], 0
	v_mov_b64_e32 v[46:47], 0
	v_mov_b64_e32 v[48:49], 0
	v_mov_b64_e32 v[50:51], 0
	v_mov_b64_e32 v[52:53], 0
	v_mov_b64_e32 v[54:55], 0
	v_mov_b64_e32 v[56:57], 0
	v_mov_b64_e32 v[58:59], 0
	v_mov_b64_e32 v[60:61], 0
	v_mov_b64_e32 v[62:63], 0
	v_mov_b64_e32 v[64:65], 0

; template <class Epi, class Sched>
; DI void gemm_phase(LAS unsigned char* lds, const Gemm g, const Sched& S, const Epi& E) {
;     ...
; #pragma unroll
;         for (int a = 0; a < 2; ++a)
; #pragma unroll
;             for (int b = 0; b < 2; ++b)
; #pragma unroll
;                 for (int m = 0; m < 4; ++m)
; #pragma unroll
;                     for (int n = 0; n < 2; ++n) acc[a][b][m][n] = (f32x4){0.f, 0.f, 0.f, 0.f};
;         cur = nxt; cA = nA; cB = nB; ++ui;
.LBB0_570:
	s_add_u32 s71, s36, 0x100
	s_addc_u32 s78, s37, 0
	s_mov_b32 s79, -2
	v_mov_b64_e32 v[2:3], 0
	v_mov_b64_e32 v[4:5], 0
	v_mov_b64_e32 v[6:7], 0
	v_mov_b64_e32 v[8:9], 0
	v_mov_b64_e32 v[10:11], 0
	v_mov_b64_e32 v[12:13], 0
	v_mov_b64_e32 v[14:15], 0
	v_mov_b64_e32 v[16:17], 0
	v_mov_b64_e32 v[18:19], 0
	v_mov_b64_e32 v[20:21], 0
	v_mov_b64_e32 v[22:23], 0
	v_mov_b64_e32 v[24:25], 0
	v_mov_b64_e32 v[26:27], 0
	v_mov_b64_e32 v[28:29], 0
	v_mov_b64_e32 v[30:31], 0
	v_mov_b64_e32 v[32:33], 0
	v_mov_b64_e32 v[34:35], 0
	v_mov_b64_e32 v[36:37], 0
	v_mov_b64_e32 v[38:39], 0
	v_mov_b64_e32 v[40:41], 0
	v_mov_b64_e32 v[42:43], 0
	v_mov_b64_e32 v[44:45], 0
	v_mov_b64_e32 v[46:47], 0
	v_mov_b64_e32 v[48:49], 0
	v_mov_b64_e32 v[50:51], 0
	v_mov_b64_e32 v[52:53], 0
	v_mov_b64_e32 v[54:55], 0
	v_mov_b64_e32 v[56:57], 0
	v_mov_b64_e32 v[58:59], 0
	v_mov_b64_e32 v[60:61], 0
	v_mov_b64_e32 v[62:63], 0
	v_mov_b64_e32 v[64:65], 0
	v_mov_b64_e32 v[66:67], 0
	v_mov_b64_e32 v[68:69], 0
	v_mov_b64_e32 v[70:71], 0
	v_mov_b64_e32 v[72:73], 0
	v_mov_b64_e32 v[74:75], 0
	v_mov_b64_e32 v[76:77], 0
	v_mov_b64_e32 v[78:79], 0
	v_mov_b64_e32 v[80:81], 0
	v_mov_b64_e32 v[82:83], 0
	v_mov_b64_e32 v[84:85], 0
	v_mov_b64_e32 v[86:87], 0
	v_mov_b64_e32 v[88:89], 0
	v_mov_b64_e32 v[90:91], 0
	v_mov_b64_e32 v[92:93], 0
	v_mov_b64_e32 v[94:95], 0
	v_mov_b64_e32 v[96:97], 0
	v_mov_b64_e32 v[98:99], 0
	v_mov_b64_e32 v[100:101], 0
	v_mov_b64_e32 v[102:103], 0
	v_mov_b64_e32 v[104:105], 0
	v_mov_b64_e32 v[106:107], 0
	v_mov_b64_e32 v[108:109], 0
	v_mov_b64_e32 v[110:111], 0
	v_mov_b64_e32 v[112:113], 0
	v_mov_b64_e32 v[114:115], 0
	v_mov_b64_e32 v[116:117], 0
	v_mov_b64_e32 v[118:119], 0
	v_mov_b64_e32 v[120:121], 0
	v_mov_b64_e32 v[122:123], 0
	v_mov_b64_e32 v[124:125], 0
	v_mov_b64_e32 v[126:127], 0
	v_mov_b64_e32 v[128:129], 0

; template <class Epi, class Sched>
; DI void gemm_phase(LAS unsigned char* lds, const Gemm g, const Sched& S, const Epi& E) {
;     ...
;         const char* nA = has_next ? (const char*)g.A + (size_t)nxt.z * g.zA * 2 + (size_t)nxt.pm * 2 * hstepA : cA;
;         const char* nB = has_next ? (const char*)g.Bt + (size_t)nxt.z * g.zB * 2 + (size_t)nxt.pn * 2 * hstepB : cB;
;     ...
; #pragma unroll
;         for (int a = 0; a < 2; ++a)
; #pragma unroll
;             for (int b = 0; b < 2; ++b)
; #pragma unroll
;                 for (int m = 0; m < 4; ++m)
; #pragma unroll
;                     for (int n = 0; n < 2; ++n) acc[a][b][m][n] = (f32x4){0.f, 0.f, 0.f, 0.f};
.LBB0_642:
	s_ashr_i32 s69, s68, 31
	s_lshl_b64 s[38:39], s[68:69], 18
	s_add_u32 s70, s12, s38
	s_addc_u32 s71, s13, s39
	s_and_b64 s[38:39], s[84:85], exec
	s_cselect_b32 s69, s71, s31
	s_cselect_b32 s74, s70, s30
	s_ashr_i32 s67, s66, 31
	s_lshl_b64 s[38:39], s[66:67], 18
	s_add_u32 s72, s14, s38
	s_addc_u32 s73, s15, s39
	s_and_b64 s[38:39], s[84:85], exec
	s_cselect_b32 s67, s73, s37
	s_cselect_b32 s75, s72, s36
	s_add_u32 s30, s30, 0x20080
	s_addc_u32 s31, s31, 0
	s_add_u32 s76, s36, 0x100
	s_addc_u32 s77, s37, 0
	s_mov_b32 s78, -2
	v_mov_b64_e32 v[2:3], 0
	v_mov_b64_e32 v[4:5], 0
	v_mov_b64_e32 v[6:7], 0
	v_mov_b64_e32 v[8:9], 0
	v_mov_b64_e32 v[10:11], 0
	v_mov_b64_e32 v[12:13], 0
	v_mov_b64_e32 v[14:15], 0
	v_mov_b64_e32 v[16:17], 0
	v_mov_b64_e32 v[18:19], 0
	v_mov_b64_e32 v[20:21], 0
	v_mov_b64_e32 v[22:23], 0
	v_mov_b64_e32 v[24:25], 0
	v_mov_b64_e32 v[26:27], 0
	v_mov_b64_e32 v[28:29], 0
	v_mov_b64_e32 v[30:31], 0
	v_mov_b64_e32 v[32:33], 0
	v_mov_b64_e32 v[34:35], 0
	v_mov_b64_e32 v[36:37], 0
	v_mov_b64_e32 v[38:39], 0
	v_mov_b64_e32 v[40:41], 0
	v_mov_b64_e32 v[42:43], 0
	v_mov_b64_e32 v[44:45], 0
	v_mov_b64_e32 v[46:47], 0
	v_mov_b64_e32 v[48:49], 0
	v_mov_b64_e32 v[50:51], 0
	v_mov_b64_e32 v[52:53], 0
	v_mov_b64_e32 v[54:55], 0
	v_mov_b64_e32 v[56:57], 0
	v_mov_b64_e32 v[58:59], 0
	v_mov_b64_e32 v[60:61], 0
	v_mov_b64_e32 v[62:63], 0
	v_mov_b64_e32 v[64:65], 0
	v_mov_b64_e32 v[66:67], 0
	v_mov_b64_e32 v[68:69], 0
	v_mov_b64_e32 v[70:71], 0
	v_mov_b64_e32 v[72:73], 0
	v_mov_b64_e32 v[74:75], 0
	v_mov_b64_e32 v[76:77], 0
	v_mov_b64_e32 v[78:79], 0
	v_mov_b64_e32 v[80:81], 0
	v_mov_b64_e32 v[82:83], 0
	v_mov_b64_e32 v[84:85], 0
	v_mov_b64_e32 v[86:87], 0
	v_mov_b64_e32 v[88:89], 0
	v_mov_b64_e32 v[90:91], 0
	v_mov_b64_e32 v[92:93], 0
	v_mov_b64_e32 v[94:95], 0
	v_mov_b64_e32 v[96:97], 0
	v_mov_b64_e32 v[98:99], 0
	v_mov_b64_e32 v[100:101], 0
	v_mov_b64_e32 v[102:103], 0
	v_mov_b64_e32 v[104:105], 0
	v_mov_b64_e32 v[106:107], 0
	v_mov_b64_e32 v[108:109], 0
	v_mov_b64_e32 v[110:111], 0
	v_mov_b64_e32 v[112:113], 0
	v_mov_b64_e32 v[114:115], 0
	v_mov_b64_e32 v[116:117], 0
	v_mov_b64_e32 v[118:119], 0
	v_mov_b64_e32 v[120:121], 0
	v_mov_b64_e32 v[122:123], 0
	v_mov_b64_e32 v[124:125], 0
	v_mov_b64_e32 v[126:127], 0
	v_mov_b64_e32 v[128:129], 0

; #define PG8_WAIT_V(n) asm volatile("s_waitcnt vmcnt(" #n ")" ::: "memory")
; #define PG8_BAR __builtin_amdgcn_s_barrier()
; #define GM_STAGE(bufoff, gbase, R2, ld_) do { _Pragma("unroll") for (int _i = 0; _i < 2; ++_i) \
;         __builtin_amdgcn_global_load_lds((const unsigned*)((const char*)(gbase) + (size_t)_i * 128 * (size_t)(ld_) + ((R2) * (unsigned)(ld_) + C2)), (LAS unsigned*)(lds + (bufoff) + ldsw + _i * 8192), 16, 0, 0); } while (0)
; #define PG8_WAIT_V(n) asm volatile("s_waitcnt vmcnt(" #n ")" ::: "memory")
; #define PG8_BAR __builtin_amdgcn_s_barrier()
; DI void gemm_phase_gm(LAS unsigned char* lds, const GmArgs ga, const SchedGM& S) {
;     ...
;     f32x4 acc[2][2][4][2];
; #pragma unroll
;     for (int a = 0; a < 2; ++a)
; #pragma unroll
;         for (int b = 0; b < 2; ++b)
; #pragma unroll
;             for (int m = 0; m < 4; ++m)
; #pragma unroll
;                 for (int n = 0; n < 2; ++n) acc[a][b][m][n] = (f32x4){0.f, 0.f, 0.f, 0.f};
;     ...
;     gm_unit_info(ga, cur, cA, cB, ldc_, nt);
;     size_t hsc = (size_t)HALF * ldc_ * 2;
;     GM_STAGE(PG8_SB(0, 0), cB, RB2, ldc_); GM_STAGE(PG8_SB(0, 1), cB + hsc, RB2, ldc_); GM_STAGE(PG8_SA(0, 0), cA, RA2, ldc_); GM_STAGE(PG8_SA(0, 1), cA + hsc, RA2, ldc_);
;     if (wr == 1) PG8_BAR;
;     PG8_WAIT_V(2); PG8_BAR;
;     GM_STAGE(PG8_SB(1, 0), cB + kstep, RB2, ldc_); GM_STAGE(PG8_SA(1, 0), cA + kstep, RA2, ldc_); GM_STAGE(PG8_SB(1, 1), cB + hsc + kstep, RB2, ldc_);
;     PG8_WAIT_V(6); PG8_BAR;
.LBB0_826:
	s_add_u32 s16, s36, 0x9a00000
	v_writelane_b32 v253, s16, 11
	s_addc_u32 s16, s37, 0
	v_writelane_b32 v253, s16, 38
	s_add_u32 s16, s44, 0x2600000
	v_writelane_b32 v253, s16, 39
	s_addc_u32 s16, s45, 0
	s_add_u32 s70, s50, 0xfa00000
	v_and_b32_e32 v0, 15, v6
	v_lshlrev_b32_e32 v250, 1, v9
	v_lshrrev_b32_e32 v9, 1, v6
	s_addc_u32 s71, s51, 0
	v_lshl_or_b32 v247, s15, 6, v0
	v_and_b32_e32 v9, 24, v9
	s_lshl_b32 s14, s14, 5
	v_writelane_b32 v253, s16, 9
	v_lshlrev_b32_e32 v10, 1, v9
	v_lshlrev_b32_e32 v12, 2, v247
	s_and_b32 s16, s14, 0x60
	v_lshlrev_b32_e32 v6, 2, v6
	v_lshl_or_b32 v0, v0, 6, v10
	s_lshl_b32 s15, s15, 13
	v_and_b32_e32 v10, 32, v12
	s_lshl_b32 s14, s16, 7
	v_and_b32_e32 v6, 32, v6
	v_bitop3_b32 v13, v0, s15, v10 bitop3:0xde
	v_bitop3_b32 v245, v0, s14, v6 bitop3:0xde
	v_lshl_add_u64 v[10:11], v[2:3], 0, s[26:27]
	s_add_i32 m0, s53, 0x18000
	s_mov_b64 s[14:15], 0x20080
	s_waitcnt vmcnt(2)
	s_barrier
	global_load_lds_dwordx4 v[10:11], off
	v_lshl_add_u64 v[10:11], v[2:3], 0, s[14:15]
	s_add_i32 m0, s53, 0x1a000
	s_add_i32 s50, s53, 0x8000
	global_load_lds_dwordx4 v[10:11], off
	v_lshl_add_u64 v[10:11], v[4:5], 0, s[26:27]
	s_mov_b32 m0, s50
	s_add_i32 s51, s53, 0xa000
	global_load_lds_dwordx4 v[10:11], off
	v_lshl_add_u64 v[4:5], v[4:5], 0, s[14:15]
	s_mov_b32 m0, s51
	s_mov_b64 s[14:15], 0x40080
	global_load_lds_dwordx4 v[4:5], off
	v_lshl_add_u64 v[4:5], v[2:3], 0, s[14:15]
	s_add_i32 m0, s53, 0x1c000
	s_mov_b64 s[14:15], 0x60080
	global_load_lds_dwordx4 v[4:5], off
	v_lshl_add_u64 v[2:3], v[2:3], 0, s[14:15]
	s_add_i32 m0, s53, 0x1e000
	s_cmpk_lt_u32 s13, 0x100
	global_load_lds_dwordx4 v[2:3], off
	v_readlane_b32 s14, v252, 60
	s_cselect_b64 s[72:73], -1, 0
	v_or_b32_e32 v246, s16, v9
	v_readlane_b32 s15, v252, 61
	s_add_u32 s14, s30, s14
	s_addc_u32 s15, s31, s15
	v_lshlrev_b32_e32 v0, 1, v246
	v_lshl_add_u64 v[2:3], s[14:15], 0, v[0:1]
	s_mov_b64 s[14:15], 0x13a00000
	v_lshlrev_b32_e32 v4, 8, v247
	v_lshl_add_u64 v[2:3], v[2:3], 0, s[14:15]
	v_ashrrev_i32_e32 v5, 31, v4
	v_or_b32_e32 v200, 16, v247
	v_lshl_add_u64 v[216:217], v[4:5], 1, v[2:3]
	v_lshlrev_b32_e32 v4, 8, v200
	v_ashrrev_i32_e32 v5, 31, v4
	v_or_b32_e32 v201, 32, v247
	v_lshl_add_u64 v[218:219], v[4:5], 1, v[2:3]
	v_lshlrev_b32_e32 v4, 8, v201
	v_ashrrev_i32_e32 v5, 31, v4
	v_or_b32_e32 v212, 48, v247
	v_lshl_add_u64 v[220:221], v[4:5], 1, v[2:3]
	v_lshlrev_b32_e32 v4, 8, v212
	v_ashrrev_i32_e32 v5, 31, v4
	v_add_u32_e32 v213, 0x80, v247
	v_lshl_add_u64 v[222:223], v[4:5], 1, v[2:3]
	v_lshlrev_b32_e32 v4, 8, v213
	v_ashrrev_i32_e32 v5, 31, v4
	v_add_u32_e32 v198, 0x90, v247
	v_lshl_add_u64 v[224:225], v[4:5], 1, v[2:3]
	v_lshlrev_b32_e32 v4, 8, v198
	v_ashrrev_i32_e32 v5, 31, v4
	v_add_u32_e32 v199, 0xa0, v247
	v_lshl_add_u64 v[226:227], v[4:5], 1, v[2:3]
	v_lshlrev_b32_e32 v4, 8, v199
	v_ashrrev_i32_e32 v5, 31, v4
	v_add_u32_e32 v210, 0xb0, v247
	v_lshl_add_u64 v[228:229], v[4:5], 1, v[2:3]
	v_lshlrev_b32_e32 v4, 8, v210
	v_ashrrev_i32_e32 v5, 31, v4
	s_waitcnt vmcnt(6)
	v_lshl_add_u64 v[230:231], v[4:5], 1, v[2:3]
	v_and_b32_e32 v0, 1, v7
	v_lshlrev_b32_e32 v2, 1, v8
	v_lshl_add_u32 v0, v0, 6, v2
	s_mov_b32 s93, 16
	v_add_u32_e32 v211, s12, v12
	s_mov_b64 s[76:77], 0x40000
	s_movk_i32 s74, 0x400
	s_mov_b32 s44, 0
	v_add_u32_e32 v208, 0, v13
	s_mov_b32 s40, 0
	v_mov_b64_e32 v[2:3], 0
	v_mov_b64_e32 v[4:5], 0
	v_mov_b64_e32 v[6:7], 0
	v_mov_b64_e32 v[8:9], 0
	v_mov_b64_e32 v[10:11], 0
	v_mov_b64_e32 v[12:13], 0
	v_mov_b64_e32 v[14:15], 0
	v_mov_b64_e32 v[16:17], 0
	v_mov_b64_e32 v[18:19], 0
	v_mov_b64_e32 v[20:21], 0
	v_mov_b64_e32 v[22:23], 0
	v_mov_b64_e32 v[24:25], 0
	v_mov_b64_e32 v[26:27], 0
	v_mov_b64_e32 v[28:29], 0
	v_mov_b64_e32 v[30:31], 0
	v_mov_b64_e32 v[32:33], 0
	v_mov_b64_e32 v[34:35], 0
	v_mov_b64_e32 v[36:37], 0
	v_mov_b64_e32 v[38:39], 0
	v_mov_b64_e32 v[40:41], 0
	v_mov_b64_e32 v[42:43], 0
	v_mov_b64_e32 v[44:45], 0
	v_mov_b64_e32 v[46:47], 0
	v_mov_b64_e32 v[48:49], 0
	v_mov_b64_e32 v[50:51], 0
	v_mov_b64_e32 v[52:53], 0
	v_mov_b64_e32 v[54:55], 0
	v_mov_b64_e32 v[56:57], 0
	v_mov_b64_e32 v[58:59], 0
	v_mov_b64_e32 v[60:61], 0
	v_mov_b64_e32 v[62:63], 0
	v_mov_b64_e32 v[64:65], 0
	v_mov_b64_e32 v[66:67], 0
	v_mov_b64_e32 v[68:69], 0
	v_mov_b64_e32 v[70:71], 0
	v_mov_b64_e32 v[72:73], 0
	v_mov_b64_e32 v[74:75], 0
	v_mov_b64_e32 v[76:77], 0
	v_mov_b64_e32 v[78:79], 0
	v_mov_b64_e32 v[80:81], 0
	v_mov_b64_e32 v[82:83], 0
	v_mov_b64_e32 v[84:85], 0
	v_mov_b64_e32 v[86:87], 0
	v_mov_b64_e32 v[88:89], 0
	v_mov_b64_e32 v[90:91], 0
	v_mov_b64_e32 v[92:93], 0
	v_mov_b64_e32 v[94:95], 0
	v_mov_b64_e32 v[96:97], 0
	v_mov_b64_e32 v[98:99], 0
	v_mov_b64_e32 v[100:101], 0
	v_mov_b64_e32 v[102:103], 0
	v_mov_b64_e32 v[104:105], 0
	v_mov_b64_e32 v[106:107], 0
	v_mov_b64_e32 v[108:109], 0
	v_mov_b64_e32 v[110:111], 0
	v_mov_b64_e32 v[112:113], 0
	v_mov_b64_e32 v[114:115], 0
	v_mov_b64_e32 v[116:117], 0
	v_mov_b64_e32 v[118:119], 0
	v_mov_b64_e32 v[120:121], 0
	v_mov_b64_e32 v[122:123], 0
	v_mov_b64_e32 v[124:125], 0
	v_mov_b64_e32 v[126:127], 0
	v_mov_b64_e32 v[128:129], 0
	s_barrier
	s_branch .LBB0_829
; #define PG8_BAR __builtin_amdgcn_s_barrier()
; #define PG8_BAR __builtin_amdgcn_s_barrier()
; DI void gemm_phase_gm(LAS unsigned char* lds, const GmArgs ga, const SchedGM& S) {
;     ...
; #pragma unroll
;         for (int a = 0; a < 2; ++a)
; #pragma unroll
;             for (int b = 0; b < 2; ++b)
; #pragma unroll
;                 for (int m = 0; m < 4; ++m)
; #pragma unroll
;                     for (int n = 0; n < 2; ++n) acc[a][b][m][n] = (f32x4){0.f, 0.f, 0.f, 0.f};
;         cur = nxt; cA = nA; cB = nB; ldc_ = ldn; nt = ntn; hsc = hsn; ++ui;
;         if (wr == 1) PG8_BAR;
.LBB0_827:
	s_mov_b32 s52, s78
	s_mov_b32 s49, s25
	s_mov_b32 s44, s41
	s_mov_b64 s[64:65], s[68:69]
	s_mov_b64 s[62:63], s[80:81]
	s_mov_b32 s74, s82
	s_mov_b32 s93, s79
	s_mov_b64 s[76:77], s[88:89]
	s_mov_b32 s40, s45
	v_mov_b64_e32 v[2:3], 0
	v_mov_b64_e32 v[4:5], 0
	v_mov_b64_e32 v[6:7], 0
	v_mov_b64_e32 v[8:9], 0
	v_mov_b64_e32 v[10:11], 0
	v_mov_b64_e32 v[12:13], 0
	v_mov_b64_e32 v[14:15], 0
	v_mov_b64_e32 v[16:17], 0
	v_mov_b64_e32 v[18:19], 0
	v_mov_b64_e32 v[20:21], 0
	v_mov_b64_e32 v[22:23], 0
	v_mov_b64_e32 v[24:25], 0
	v_mov_b64_e32 v[26:27], 0
	v_mov_b64_e32 v[28:29], 0
	v_mov_b64_e32 v[30:31], 0
	v_mov_b64_e32 v[32:33], 0
	v_mov_b64_e32 v[34:35], 0
	v_mov_b64_e32 v[36:37], 0
	v_mov_b64_e32 v[38:39], 0
	v_mov_b64_e32 v[40:41], 0
	v_mov_b64_e32 v[42:43], 0
	v_mov_b64_e32 v[44:45], 0
	v_mov_b64_e32 v[46:47], 0
	v_mov_b64_e32 v[48:49], 0
	v_mov_b64_e32 v[50:51], 0
	v_mov_b64_e32 v[52:53], 0
	v_mov_b64_e32 v[54:55], 0
	v_mov_b64_e32 v[56:57], 0
	v_mov_b64_e32 v[58:59], 0
	v_mov_b64_e32 v[60:61], 0
	v_mov_b64_e32 v[62:63], 0
	v_mov_b64_e32 v[64:65], 0
	v_mov_b64_e32 v[66:67], 0
	v_mov_b64_e32 v[68:69], 0
	v_mov_b64_e32 v[70:71], 0
	v_mov_b64_e32 v[72:73], 0
	v_mov_b64_e32 v[74:75], 0
	v_mov_b64_e32 v[76:77], 0
	v_mov_b64_e32 v[78:79], 0
	v_mov_b64_e32 v[80:81], 0
	v_mov_b64_e32 v[82:83], 0
	v_mov_b64_e32 v[84:85], 0
	v_mov_b64_e32 v[86:87], 0
	v_mov_b64_e32 v[88:89], 0
	v_mov_b64_e32 v[90:91], 0
	v_mov_b64_e32 v[92:93], 0
	v_mov_b64_e32 v[94:95], 0
	v_mov_b64_e32 v[96:97], 0
	v_mov_b64_e32 v[98:99], 0
	v_mov_b64_e32 v[100:101], 0
	v_mov_b64_e32 v[102:103], 0
	v_mov_b64_e32 v[104:105], 0
	v_mov_b64_e32 v[106:107], 0
	v_mov_b64_e32 v[108:109], 0
	v_mov_b64_e32 v[110:111], 0
	v_mov_b64_e32 v[112:113], 0
	v_mov_b64_e32 v[114:115], 0
	v_mov_b64_e32 v[116:117], 0
	v_mov_b64_e32 v[118:119], 0
	v_mov_b64_e32 v[120:121], 0
	v_mov_b64_e32 v[122:123], 0
	v_mov_b64_e32 v[124:125], 0
	v_mov_b64_e32 v[126:127], 0
	v_mov_b64_e32 v[128:129], 0

; template <class Epi, class Sched>
; DI void gemm_phase(LAS unsigned char* lds, const Gemm g, const Sched& S, const Epi& E) {
;     ...
;         const char* nA = has_next ? (const char*)g.A + (size_t)nxt.z * g.zA * 2 + (size_t)nxt.pm * 2 * hstepA : cA;
;         const char* nB = has_next ? (const char*)g.Bt + (size_t)nxt.z * g.zB * 2 + (size_t)nxt.pn * 2 * hstepB : cB;
;     ...
; #pragma unroll
;         for (int a = 0; a < 2; ++a)
; #pragma unroll
;             for (int b = 0; b < 2; ++b)
; #pragma unroll
;                 for (int m = 0; m < 4; ++m)
; #pragma unroll
;                     for (int n = 0; n < 2; ++n) acc[a][b][m][n] = (f32x4){0.f, 0.f, 0.f, 0.f};
.LBB0_953:
	s_ashr_i32 s77, s76, 31
	s_lshl_b64 s[40:41], s[76:77], 19
	s_add_u32 s78, s12, s40
	s_addc_u32 s79, s13, s41
	s_and_b64 s[40:41], s[96:97], exec
	s_cselect_b32 s28, s79, s39
	s_cselect_b32 s31, s78, s38
	s_ashr_i32 s75, s74, 31
	s_lshl_b64 s[40:41], s[74:75], 19
	s_add_u32 s80, s14, s40
	s_addc_u32 s81, s15, s41
	s_and_b64 s[40:41], s[96:97], exec
	s_cselect_b32 s40, s81, s37
	s_cselect_b32 s41, s80, s36
	s_add_u32 s44, s38, 0x40080
	s_addc_u32 s45, s39, 0
	s_add_u32 s75, s36, 0x100
	s_addc_u32 s77, s37, 0
	s_mov_b32 s88, -2
	v_mov_b64_e32 v[2:3], 0
	v_mov_b64_e32 v[4:5], 0
	v_mov_b64_e32 v[6:7], 0
	v_mov_b64_e32 v[8:9], 0
	v_mov_b64_e32 v[10:11], 0
	v_mov_b64_e32 v[12:13], 0
	v_mov_b64_e32 v[14:15], 0
	v_mov_b64_e32 v[16:17], 0
	v_mov_b64_e32 v[18:19], 0
	v_mov_b64_e32 v[20:21], 0
	v_mov_b64_e32 v[22:23], 0
	v_mov_b64_e32 v[24:25], 0
	v_mov_b64_e32 v[26:27], 0
	v_mov_b64_e32 v[28:29], 0
	v_mov_b64_e32 v[30:31], 0
	v_mov_b64_e32 v[32:33], 0
	v_mov_b64_e32 v[34:35], 0
	v_mov_b64_e32 v[36:37], 0
	v_mov_b64_e32 v[38:39], 0
	v_mov_b64_e32 v[40:41], 0
	v_mov_b64_e32 v[42:43], 0
	v_mov_b64_e32 v[44:45], 0
	v_mov_b64_e32 v[46:47], 0
	v_mov_b64_e32 v[48:49], 0
	v_mov_b64_e32 v[50:51], 0
	v_mov_b64_e32 v[52:53], 0
	v_mov_b64_e32 v[54:55], 0
	v_mov_b64_e32 v[56:57], 0
	v_mov_b64_e32 v[58:59], 0
	v_mov_b64_e32 v[60:61], 0
	v_mov_b64_e32 v[62:63], 0
	v_mov_b64_e32 v[64:65], 0
	v_mov_b64_e32 v[66:67], 0
	v_mov_b64_e32 v[68:69], 0
	v_mov_b64_e32 v[70:71], 0
	v_mov_b64_e32 v[72:73], 0
	v_mov_b64_e32 v[74:75], 0
	v_mov_b64_e32 v[76:77], 0
	v_mov_b64_e32 v[86:87], 0
	v_mov_b64_e32 v[88:89], 0
	v_mov_b64_e32 v[90:91], 0
	v_mov_b64_e32 v[92:93], 0
	v_mov_b64_e32 v[102:103], 0
	v_mov_b64_e32 v[104:105], 0
	v_mov_b64_e32 v[106:107], 0
	v_mov_b64_e32 v[108:109], 0
	v_mov_b64_e32 v[110:111], 0
	v_mov_b64_e32 v[112:113], 0
	v_mov_b64_e32 v[114:115], 0
	v_mov_b64_e32 v[116:117], 0
	v_mov_b64_e32 v[118:119], 0
	v_mov_b64_e32 v[120:121], 0
	v_mov_b64_e32 v[122:123], 0
	v_mov_b64_e32 v[124:125], 0
	v_mov_b64_e32 v[126:127], 0
	v_mov_b64_e32 v[128:129], 0
	v_mov_b64_e32 v[130:131], 0
	v_mov_b64_e32 v[132:133], 0
	v_mov_b64_e32 v[134:135], 0
	v_mov_b64_e32 v[136:137], 0
	v_mov_b64_e32 v[138:139], 0
	v_mov_b64_e32 v[140:141], 0
	v_mov_b64_e32 v[142:143], 0
	v_mov_b64_e32 v[144:145], 0

;     DI bool next(int i, Unit& u) const { const long L = (long)i * G + c; if (L >= (long)nM * nN) return false; tile_decode((int)L, nM, nN, u.pm, u.pn); u.z = 0; return true; }
; #define PG8_WAIT_V(n) asm volatile("s_waitcnt vmcnt(" #n ")" ::: "memory")
; template <class Epi, class Sched>
; DI void gemm_phase(LAS unsigned char* lds, const Gemm g, const Sched& S, const Epi& E) {
;     ...
;     for (int i = 0; i < 2; ++i) { int R, C; stage_rc(tid * 16 + i * 8192, R, C); const int Rb = (R & ~31) + perm32(R & 31);
;         voffA[i] = (unsigned)(R * g.lda + C) * 2u; voffB[i] = (unsigned)(Rb * g.ldb + C) * 2u; }
;     const size_t kstep = (size_t)(BK * 2);
;     const size_t hstepA = (size_t)HALF * g.lda * 2, hstepB = (size_t)HALF * g.ldb * 2;
;     const unsigned ldsw = (unsigned)wid * 1024u;
;     const int aoff = lds_byte(wr * 64 + fr, fq * 8), boff = lds_byte(wc * 32 + fr, fq * 8);
;     ...
;     Unit cur, nxt; int ui = 0;
;     if (!S.next(0, cur)) return;
;     ...
;     if constexpr (Epi::NEEDS_R) {
;         Unit uu; for (int i = 0; i < 8 && S.next(i, uu); ++i) PG8_RFILL(uu, i);
;     }
;     f32x4 acc[2][2][4][2];
; #pragma unroll
;     for (int a = 0; a < 2; ++a)
; #pragma unroll
;         for (int b = 0; b < 2; ++b)
; #pragma unroll
;             for (int m = 0; m < 4; ++m)
; #pragma unroll
;                 for (int n = 0; n < 2; ++n) acc[a][b][m][n] = (f32x4){0.f, 0.f, 0.f, 0.f};
;     bf16x8 At[4][2], B0[2][2], B1[2][2];
;     const char* cA = (const char*)g.A + (size_t)cur.z * g.zA * 2 + (size_t)cur.pm * 2 * hstepA;
;     const char* cB = (const char*)g.Bt + (size_t)cur.z * g.zB * 2 + (size_t)cur.pn * 2 * hstepB;
;     PG8_STAGE(PG8_SB(0, 0), cB, voffB); PG8_STAGE(PG8_SB(0, 1), cB + hstepB, voffB); PG8_STAGE(PG8_SA(0, 0), cA, voffA); PG8_STAGE(PG8_SA(0, 1), cA + hstepA, voffA);
;     if (wr == 1) PG8_BAR;
;     PG8_WAIT_V(2); PG8_BAR;
;     PG8_STAGE(PG8_SB(1, 0), cB + kstep, voffB); PG8_STAGE(PG8_SA(1, 0), cA + kstep, voffA); PG8_STAGE(PG8_SB(1, 1), cB + hstepB + kstep, voffB);
;     PG8_WAIT_V(6); PG8_BAR;
;     ...
; #pragma unroll
;         for (int a = 0; a < 2; ++a)
; #pragma unroll
;             for (int b = 0; b < 2; ++b)
; #pragma unroll
;                 for (int m = 0; m < 4; ++m)
; #pragma unroll
;                     for (int n = 0; n < 2; ++n) acc[a][b][m][n] = (f32x4){0.f, 0.f, 0.f, 0.f};
;         cur = nxt; cA = nA; cB = nB; ++ui;
.LBB0_1057:
	v_and_b32_e32 v17, 15, v10
	v_lshrrev_b32_e32 v10, 1, v10
	v_and_b32_e32 v10, 24, v10
	v_lshlrev_b32_e32 v18, 1, v10
	s_add_u32 s68, s36, 0x9a00000
	v_lshl_or_b32 v144, s38, 6, v17
	v_lshl_or_b32 v18, v17, 6, v18
	v_lshlrev_b32_e32 v17, 2, v17
	s_addc_u32 s69, s37, 0
	s_lshl_b32 s36, s38, 13
	v_and_b32_e32 v19, 32, v17
	v_bitop3_b32 v20, v18, s36, v19 bitop3:0xde
	s_lshl_b32 s36, s39, 5
	s_and_b32 s39, s36, 0x60
	s_add_i32 m0, s17, 0x18000
	v_lshl_add_u64 v[8:9], v[8:9], 0, s[26:27]
	s_lshl_b32 s36, s39, 7
	s_waitcnt vmcnt(2)
	s_barrier
	global_load_lds_dwordx4 v[8:9], off
	v_lshl_add_u64 v[6:7], v[6:7], 0, s[26:27]
	s_add_i32 m0, s17, 0x1a000
	s_add_i32 s41, s17, 0x8000
	s_add_i32 s44, s17, 0xa000
	v_bitop3_b32 v145, v18, s36, v19 bitop3:0xde
	global_load_lds_dwordx4 v[6:7], off
	v_lshl_add_u64 v[4:5], v[4:5], 0, s[26:27]
	s_mov_b32 m0, s41
	s_add_u32 s36, s30, 0x40080
	global_load_lds_dwordx4 v[4:5], off
	v_lshl_add_u64 v[2:3], v[2:3], 0, s[26:27]
	s_mov_b32 m0, s44
	s_addc_u32 s37, s31, 0
	global_load_lds_dwordx4 v[2:3], off
	s_add_i32 m0, s17, 0x1c000
	v_lshl_add_u64 v[2:3], s[36:37], 0, v[0:1]
	global_load_lds_dwordx4 v[2:3], off
	v_lshl_add_u64 v[2:3], s[36:37], 0, v[134:135]
	s_add_i32 m0, s17, 0x1e000
	s_lshl_b32 s36, s38, 8
	global_load_lds_dwordx4 v[2:3], off
	v_lshlrev_b32_e32 v2, 14, v11
	v_and_b32_e32 v2, 0xffff8000, v2
	v_lshl_add_u32 v2, v12, 11, v2
	v_and_b32_e32 v3, 1, v11
	v_lshl_or_b32 v2, v3, 6, v2
	v_lshl_add_u32 v136, v13, 1, v2
	v_lshlrev_b32_e32 v2, 14, v14
	v_and_b32_e32 v2, 0xffff8000, v2
	s_add_i32 s36, s36, 0
	v_lshl_add_u32 v2, v15, 11, v2
	v_and_b32_e32 v3, 1, v14
	s_waitcnt vmcnt(6)
	s_add_i32 s36, s36, 0x20000
	v_lshl_or_b32 v2, v3, 6, v2
	s_cmpk_lt_u32 s49, 0x100
	v_lshl_add_u32 v138, v16, 1, v2
	v_add_u32_e32 v146, s36, v17
	s_cselect_b64 s[70:71], -1, 0
	v_or_b32_e32 v147, s39, v10
	v_mov_b32_e32 v137, v1
	v_mov_b32_e32 v139, v1
	s_mov_b32 s45, 0
	v_add_u32_e32 v148, 0, v20
	v_mov_b64_e32 v[2:3], 0
	v_mov_b64_e32 v[4:5], 0
	v_mov_b64_e32 v[6:7], 0
	v_mov_b64_e32 v[8:9], 0
	v_mov_b64_e32 v[10:11], 0
	v_mov_b64_e32 v[12:13], 0
	v_mov_b64_e32 v[14:15], 0
	v_mov_b64_e32 v[16:17], 0
	v_mov_b64_e32 v[18:19], 0
	v_mov_b64_e32 v[20:21], 0
	v_mov_b64_e32 v[22:23], 0
	v_mov_b64_e32 v[24:25], 0
	v_mov_b64_e32 v[26:27], 0
	v_mov_b64_e32 v[28:29], 0
	v_mov_b64_e32 v[30:31], 0
	v_mov_b64_e32 v[32:33], 0
	v_mov_b64_e32 v[34:35], 0
	v_mov_b64_e32 v[36:37], 0
	v_mov_b64_e32 v[38:39], 0
	v_mov_b64_e32 v[40:41], 0
	v_mov_b64_e32 v[42:43], 0
	v_mov_b64_e32 v[44:45], 0
	v_mov_b64_e32 v[46:47], 0
	v_mov_b64_e32 v[48:49], 0
	v_mov_b64_e32 v[50:51], 0
	v_mov_b64_e32 v[52:53], 0
	v_mov_b64_e32 v[54:55], 0
	v_mov_b64_e32 v[56:57], 0
	v_mov_b64_e32 v[58:59], 0
	v_mov_b64_e32 v[60:61], 0
	v_mov_b64_e32 v[62:63], 0
	v_mov_b64_e32 v[64:65], 0
	v_mov_b64_e32 v[66:67], 0
	v_mov_b64_e32 v[68:69], 0
	v_mov_b64_e32 v[70:71], 0
	v_mov_b64_e32 v[72:73], 0
	v_mov_b64_e32 v[74:75], 0
	v_mov_b64_e32 v[76:77], 0
	v_mov_b64_e32 v[78:79], 0
	v_mov_b64_e32 v[80:81], 0
	v_mov_b64_e32 v[82:83], 0
	v_mov_b64_e32 v[84:85], 0
	v_mov_b64_e32 v[86:87], 0
	v_mov_b64_e32 v[88:89], 0
	v_mov_b64_e32 v[90:91], 0
	v_mov_b64_e32 v[92:93], 0
	v_mov_b64_e32 v[94:95], 0
	v_mov_b64_e32 v[96:97], 0
	v_mov_b64_e32 v[98:99], 0
	v_mov_b64_e32 v[100:101], 0
	v_mov_b64_e32 v[102:103], 0
	v_mov_b64_e32 v[104:105], 0
	v_mov_b64_e32 v[106:107], 0
	v_mov_b64_e32 v[108:109], 0
	v_mov_b64_e32 v[110:111], 0
	v_mov_b64_e32 v[112:113], 0
	v_mov_b64_e32 v[114:115], 0
	v_mov_b64_e32 v[116:117], 0
	v_mov_b64_e32 v[118:119], 0
	v_mov_b64_e32 v[120:121], 0
	v_mov_b64_e32 v[122:123], 0
	v_mov_b64_e32 v[124:125], 0
	v_mov_b64_e32 v[126:127], 0
	v_mov_b64_e32 v[128:129], 0
	s_barrier
	s_branch .LBB0_1059
.LBB0_1058:
	s_mov_b32 s62, s76
	s_mov_b32 s64, s74
	v_mov_b64_e32 v[2:3], 0
	v_mov_b64_e32 v[4:5], 0
	v_mov_b64_e32 v[6:7], 0
	v_mov_b64_e32 v[8:9], 0
	v_mov_b64_e32 v[10:11], 0
	v_mov_b64_e32 v[12:13], 0
	v_mov_b64_e32 v[14:15], 0
	v_mov_b64_e32 v[16:17], 0
	v_mov_b64_e32 v[18:19], 0
	v_mov_b64_e32 v[20:21], 0
	v_mov_b64_e32 v[22:23], 0
	v_mov_b64_e32 v[24:25], 0
	v_mov_b64_e32 v[26:27], 0
	v_mov_b64_e32 v[28:29], 0
	v_mov_b64_e32 v[30:31], 0
	v_mov_b64_e32 v[32:33], 0
	v_mov_b64_e32 v[34:35], 0
	v_mov_b64_e32 v[36:37], 0
	v_mov_b64_e32 v[38:39], 0
	v_mov_b64_e32 v[40:41], 0
	v_mov_b64_e32 v[42:43], 0
	v_mov_b64_e32 v[44:45], 0
	v_mov_b64_e32 v[46:47], 0
	v_mov_b64_e32 v[48:49], 0
	v_mov_b64_e32 v[50:51], 0
	v_mov_b64_e32 v[52:53], 0
	v_mov_b64_e32 v[54:55], 0
	v_mov_b64_e32 v[56:57], 0
	v_mov_b64_e32 v[58:59], 0
	v_mov_b64_e32 v[60:61], 0
	v_mov_b64_e32 v[62:63], 0
	v_mov_b64_e32 v[64:65], 0
	v_mov_b64_e32 v[66:67], 0
	v_mov_b64_e32 v[68:69], 0
	v_mov_b64_e32 v[70:71], 0
	v_mov_b64_e32 v[72:73], 0
	v_mov_b64_e32 v[74:75], 0
	v_mov_b64_e32 v[76:77], 0
	v_mov_b64_e32 v[78:79], 0
	v_mov_b64_e32 v[80:81], 0
	v_mov_b64_e32 v[82:83], 0
	v_mov_b64_e32 v[84:85], 0
	v_mov_b64_e32 v[86:87], 0
	v_mov_b64_e32 v[88:89], 0
	v_mov_b64_e32 v[90:91], 0
	v_mov_b64_e32 v[92:93], 0
	v_mov_b64_e32 v[94:95], 0
	v_mov_b64_e32 v[96:97], 0
	v_mov_b64_e32 v[98:99], 0
	v_mov_b64_e32 v[100:101], 0
	v_mov_b64_e32 v[102:103], 0
	v_mov_b64_e32 v[104:105], 0
	v_mov_b64_e32 v[106:107], 0
	v_mov_b64_e32 v[108:109], 0
	v_mov_b64_e32 v[110:111], 0
	v_mov_b64_e32 v[112:113], 0
	v_mov_b64_e32 v[114:115], 0
	v_mov_b64_e32 v[116:117], 0
	v_mov_b64_e32 v[118:119], 0
	v_mov_b64_e32 v[120:121], 0
	v_mov_b64_e32 v[122:123], 0
	v_mov_b64_e32 v[124:125], 0
	v_mov_b64_e32 v[126:127], 0
	v_mov_b64_e32 v[128:129], 0
	s_mov_b64 s[72:73], s[80:81]
	s_mov_b32 s45, s49
	s_andn2_b64 vcc, exec, s[84:85]
	s_mov_b64 s[30:31], s[78:79]
	s_cbranch_vccz .LBB0_1073

;     DI bool next(int i, Unit& u) const { const long L = (long)i * G + c; if (L >= (long)nM * nN) return false; tile_decode((int)L, nM, nN, u.pm, u.pn); u.z = 0; return true; }
;     DI bool next(int i, Unit& u) const { const long L = (long)i * G + c; if (L >= (long)nZ * nM * nN) return false; const int l = (int)L; u.z = l / (nM * nN); const int r = l % (nM * nN); u.pm = r / nN; u.pn = r % nN; return true; }
;     DI bool next(int i, Unit& u) const { const long L = (long)(i / 3) * G + c; if (L >= (long)nM * nN) return false; tile_decode((int)L, nM, nN, u.pm, u.pn); u.z = i % 3; return true; }
; #define PG8_STAGE(bufoff, gbase, voff) do { _Pragma("unroll") for (int _i = 0; _i < 2; ++_i) \
;         __builtin_amdgcn_global_load_lds((const unsigned*)((const char*)(gbase) + (voff)[_i]), (LAS unsigned*)(lds + (bufoff) + ldsw + _i * 8192), 16, 0, 0); } while (0)
; #define PG8_LDA(dst, b, h) do { _Pragma("unroll") for (int m = 0; m < 4; ++m) _Pragma("unroll") for (int k = 0; k < 2; ++k) dst[m][k] = *(const LAS bf16x8*)(lds + PG8_SA(b, h) + aoff + m * 2048 + k * 1024); } while (0)
; #define PG8_SCHED __builtin_amdgcn_sched_barrier(0)
; template <class Epi, class Sched>
; DI void gemm_phase(LAS unsigned char* lds, const Gemm g, const Sched& S, const Epi& E) {
;     ...
;         const bool has_next = S.next(ui + 1, nxt);
;         const char* nA = has_next ? (const char*)g.A + (size_t)nxt.z * g.zA * 2 + (size_t)nxt.pm * 2 * hstepA : cA;
;         const char* nB = has_next ? (const char*)g.Bt + (size_t)nxt.z * g.zB * 2 + (size_t)nxt.pn * 2 * hstepB : cB;
;         for (int t = 0; t < nt; t += 2) {
;             const bool last = (t == nt - 2);
;             const char* a1 = cA + (size_t)(t + 1) * kstep;
;             const char* a2 = last ? nA : cA + (size_t)(t + 2) * kstep; const char* b2 = last ? nB : cB + (size_t)(t + 2) * kstep;
;             const char* a3 = a2 + kstep; const char* b3 = b2 + kstep;
;             PG8_LDB(B0, 0, 0); PG8_LDB(B1, 0, 1); PG8_SCHED; PG8_LDA(At, 0, 0); PG8_STAGE(PG8_SA(1, 1), a1 + hstepA, voffA);
;     ...
; #pragma unroll
;         for (int a = 0; a < 2; ++a)
; #pragma unroll
;             for (int b = 0; b < 2; ++b)
; #pragma unroll
;                 for (int m = 0; m < 4; ++m)
; #pragma unroll
;                     for (int n = 0; n < 2; ++n) acc[a][b][m][n] = (f32x4){0.f, 0.f, 0.f, 0.f};
;         cur = nxt; cA = nA; cB = nB; ++ui;
.LBB0_1252:
	s_ashr_i32 s73, s72, 31
	s_lshl_b64 s[40:41], s[72:73], 18
	s_add_u32 s74, s12, s40
	s_addc_u32 s75, s13, s41
	s_and_b64 s[40:41], s[94:95], exec
	s_cselect_b32 s28, s75, s39
	s_cselect_b32 s40, s74, s38
	s_ashr_i32 s71, s70, 31
	s_lshl_b64 s[50:51], s[70:71], 18
	s_add_u32 s76, s14, s50
	s_addc_u32 s77, s15, s51
	s_and_b64 s[50:51], s[94:95], exec
	s_cselect_b32 s41, s77, s37
	s_cselect_b32 s45, s76, s36
	s_add_u32 s50, s38, 0x20080
	s_addc_u32 s51, s39, 0
	s_add_u32 s71, s36, 0x100
	s_addc_u32 s73, s37, 0
	s_mov_b32 s87, -2
	v_mov_b64_e32 v[2:3], 0
	v_mov_b64_e32 v[4:5], 0
	v_mov_b64_e32 v[6:7], 0
	v_mov_b64_e32 v[8:9], 0
	v_mov_b64_e32 v[10:11], 0
	v_mov_b64_e32 v[12:13], 0
	v_mov_b64_e32 v[14:15], 0
	v_mov_b64_e32 v[16:17], 0
	v_mov_b64_e32 v[18:19], 0
	v_mov_b64_e32 v[20:21], 0
	v_mov_b64_e32 v[22:23], 0
	v_mov_b64_e32 v[24:25], 0
	v_mov_b64_e32 v[26:27], 0
	v_mov_b64_e32 v[28:29], 0
	v_mov_b64_e32 v[30:31], 0
	v_mov_b64_e32 v[32:33], 0
	v_mov_b64_e32 v[34:35], 0
	v_mov_b64_e32 v[36:37], 0
	v_mov_b64_e32 v[38:39], 0
	v_mov_b64_e32 v[40:41], 0
	v_mov_b64_e32 v[42:43], 0
	v_mov_b64_e32 v[44:45], 0
	v_mov_b64_e32 v[46:47], 0
	v_mov_b64_e32 v[48:49], 0
	v_mov_b64_e32 v[50:51], 0
	v_mov_b64_e32 v[52:53], 0
	v_mov_b64_e32 v[54:55], 0
	v_mov_b64_e32 v[56:57], 0
	v_mov_b64_e32 v[58:59], 0
	v_mov_b64_e32 v[60:61], 0
	v_mov_b64_e32 v[62:63], 0
	v_mov_b64_e32 v[64:65], 0
	v_mov_b64_e32 v[66:67], 0
	v_mov_b64_e32 v[68:69], 0
	v_mov_b64_e32 v[70:71], 0
	v_mov_b64_e32 v[72:73], 0
	v_mov_b64_e32 v[74:75], 0
	v_mov_b64_e32 v[76:77], 0
	v_mov_b64_e32 v[86:87], 0
	v_mov_b64_e32 v[88:89], 0
	v_mov_b64_e32 v[90:91], 0
	v_mov_b64_e32 v[92:93], 0
	v_mov_b64_e32 v[102:103], 0
	v_mov_b64_e32 v[104:105], 0
	v_mov_b64_e32 v[106:107], 0
	v_mov_b64_e32 v[108:109], 0
	v_mov_b64_e32 v[110:111], 0
	v_mov_b64_e32 v[112:113], 0
	v_mov_b64_e32 v[114:115], 0
	v_mov_b64_e32 v[116:117], 0
	v_mov_b64_e32 v[118:119], 0
	v_mov_b64_e32 v[120:121], 0
	v_mov_b64_e32 v[122:123], 0
	v_mov_b64_e32 v[124:125], 0
	v_mov_b64_e32 v[126:127], 0
	v_mov_b64_e32 v[128:129], 0
	v_mov_b64_e32 v[130:131], 0
	v_mov_b64_e32 v[132:133], 0
	v_mov_b64_e32 v[134:135], 0
	v_mov_b64_e32 v[136:137], 0
	v_mov_b64_e32 v[138:139], 0
	v_mov_b64_e32 v[140:141], 0
	v_mov_b64_e32 v[142:143], 0
	v_mov_b64_e32 v[144:145], 0

;     DI bool next(int i, Unit& u) const { const long L = (long)i * G + c; if (L >= (long)nM * nN) return false; tile_decode((int)L, nM, nN, u.pm, u.pn); u.z = 0; return true; }
; #define PG8_WAIT_V(n) asm volatile("s_waitcnt vmcnt(" #n ")" ::: "memory")
; template <class Epi, class Sched>
; DI void gemm_phase(LAS unsigned char* lds, const Gemm g, const Sched& S, const Epi& E) {
;     ...
;     for (int i = 0; i < 2; ++i) { int R, C; stage_rc(tid * 16 + i * 8192, R, C); const int Rb = (R & ~31) + perm32(R & 31);
;         voffA[i] = (unsigned)(R * g.lda + C) * 2u; voffB[i] = (unsigned)(Rb * g.ldb + C) * 2u; }
;     const size_t kstep = (size_t)(BK * 2);
;     const size_t hstepA = (size_t)HALF * g.lda * 2, hstepB = (size_t)HALF * g.ldb * 2;
;     const unsigned ldsw = (unsigned)wid * 1024u;
;     const int aoff = lds_byte(wr * 64 + fr, fq * 8), boff = lds_byte(wc * 32 + fr, fq * 8);
;     ...
;     Unit cur, nxt; int ui = 0;
;     if (!S.next(0, cur)) return;
;     ...
;     if constexpr (Epi::NEEDS_R) {
;         Unit uu; for (int i = 0; i < 8 && S.next(i, uu); ++i) PG8_RFILL(uu, i);
;     }
;     f32x4 acc[2][2][4][2];
; #pragma unroll
;     for (int a = 0; a < 2; ++a)
; #pragma unroll
;         for (int b = 0; b < 2; ++b)
; #pragma unroll
;             for (int m = 0; m < 4; ++m)
; #pragma unroll
;                 for (int n = 0; n < 2; ++n) acc[a][b][m][n] = (f32x4){0.f, 0.f, 0.f, 0.f};
;     bf16x8 At[4][2], B0[2][2], B1[2][2];
;     const char* cA = (const char*)g.A + (size_t)cur.z * g.zA * 2 + (size_t)cur.pm * 2 * hstepA;
;     const char* cB = (const char*)g.Bt + (size_t)cur.z * g.zB * 2 + (size_t)cur.pn * 2 * hstepB;
;     PG8_STAGE(PG8_SB(0, 0), cB, voffB); PG8_STAGE(PG8_SB(0, 1), cB + hstepB, voffB); PG8_STAGE(PG8_SA(0, 0), cA, voffA); PG8_STAGE(PG8_SA(0, 1), cA + hstepA, voffA);
;     if (wr == 1) PG8_BAR;
;     PG8_WAIT_V(2); PG8_BAR;
;     PG8_STAGE(PG8_SB(1, 0), cB + kstep, voffB); PG8_STAGE(PG8_SA(1, 0), cA + kstep, voffA); PG8_STAGE(PG8_SB(1, 1), cB + hstepB + kstep, voffB);
;     PG8_WAIT_V(6); PG8_BAR;
;     ...
; #pragma unroll
;         for (int a = 0; a < 2; ++a)
; #pragma unroll
;             for (int b = 0; b < 2; ++b)
; #pragma unroll
;                 for (int m = 0; m < 4; ++m)
; #pragma unroll
;                     for (int n = 0; n < 2; ++n) acc[a][b][m][n] = (f32x4){0.f, 0.f, 0.f, 0.f};
;         cur = nxt; cA = nA; cB = nB; ++ui;
.LBB0_1356:
	v_and_b32_e32 v17, 15, v10
	v_lshrrev_b32_e32 v10, 1, v10
	v_and_b32_e32 v10, 24, v10
	s_add_u32 s62, s44, 0x9a00000
	v_lshlrev_b32_e32 v18, 1, v10
	s_addc_u32 s63, s45, 0
	v_lshl_or_b32 v144, s38, 6, v17
	v_lshl_or_b32 v18, v17, 6, v18
	v_lshlrev_b32_e32 v17, 2, v17
	s_lshl_b32 s39, s39, 5
	s_lshl_b32 s40, s38, 13
	v_and_b32_e32 v19, 32, v17
	s_and_b32 s39, s39, 0x60
	v_bitop3_b32 v20, v18, s40, v19 bitop3:0xde
	s_lshl_b32 s40, s39, 7
	s_add_i32 m0, s17, 0x18000
	v_lshl_add_u64 v[8:9], v[8:9], 0, s[26:27]
	v_bitop3_b32 v145, v18, s40, v19 bitop3:0xde
	s_waitcnt vmcnt(2)
	s_barrier
	global_load_lds_dwordx4 v[8:9], off
	v_lshl_add_u64 v[6:7], v[6:7], 0, s[26:27]
	s_add_i32 m0, s17, 0x1a000
	s_add_i32 s40, s17, 0x8000
	s_add_i32 s41, s17, 0xa000
	global_load_lds_dwordx4 v[6:7], off
	v_lshl_add_u64 v[4:5], v[4:5], 0, s[26:27]
	s_mov_b32 m0, s40
	s_add_u32 s44, s36, 0x40080
	global_load_lds_dwordx4 v[4:5], off
	v_lshl_add_u64 v[2:3], v[2:3], 0, s[26:27]
	s_mov_b32 m0, s41
	s_addc_u32 s45, s37, 0
	global_load_lds_dwordx4 v[2:3], off
	s_add_i32 m0, s17, 0x1c000
	v_lshl_add_u64 v[2:3], s[44:45], 0, v[0:1]
	global_load_lds_dwordx4 v[2:3], off
	v_lshl_add_u64 v[2:3], s[44:45], 0, v[134:135]
	s_add_i32 m0, s17, 0x1e000
	s_lshl_b32 s38, s38, 8
	global_load_lds_dwordx4 v[2:3], off
	v_lshlrev_b32_e32 v2, 14, v11
	v_and_b32_e32 v2, 0xffff8000, v2
	v_lshl_add_u32 v2, v12, 11, v2
	v_and_b32_e32 v3, 1, v11
	v_lshl_or_b32 v2, v3, 6, v2
	v_lshl_add_u32 v136, v13, 1, v2
	v_lshlrev_b32_e32 v2, 14, v14
	v_and_b32_e32 v2, 0xffff8000, v2
	s_add_i32 s38, s38, 0
	v_lshl_add_u32 v2, v15, 11, v2
	v_and_b32_e32 v3, 1, v14
	s_waitcnt vmcnt(6)
	s_add_i32 s38, s38, 0x20000
	v_lshl_or_b32 v2, v3, 6, v2
	s_cmpk_lt_u32 s64, 0x100
	v_lshl_add_u32 v138, v16, 1, v2
	v_add_u32_e32 v146, s38, v17
	s_cselect_b64 s[64:65], -1, 0
	v_or_b32_e32 v147, s39, v10
	v_mov_b32_e32 v137, v1
	v_mov_b32_e32 v139, v1
	s_mov_b32 s49, 0
	v_add_u32_e32 v148, 0, v20
	v_mov_b64_e32 v[2:3], 0
	v_mov_b64_e32 v[4:5], 0
	v_mov_b64_e32 v[6:7], 0
	v_mov_b64_e32 v[8:9], 0
	v_mov_b64_e32 v[10:11], 0
	v_mov_b64_e32 v[12:13], 0
	v_mov_b64_e32 v[14:15], 0
	v_mov_b64_e32 v[16:17], 0
	v_mov_b64_e32 v[18:19], 0
	v_mov_b64_e32 v[20:21], 0
	v_mov_b64_e32 v[22:23], 0
	v_mov_b64_e32 v[24:25], 0
	v_mov_b64_e32 v[26:27], 0
	v_mov_b64_e32 v[28:29], 0
	v_mov_b64_e32 v[30:31], 0
	v_mov_b64_e32 v[32:33], 0
	v_mov_b64_e32 v[34:35], 0
	v_mov_b64_e32 v[36:37], 0
	v_mov_b64_e32 v[38:39], 0
	v_mov_b64_e32 v[40:41], 0
	v_mov_b64_e32 v[42:43], 0
	v_mov_b64_e32 v[44:45], 0
	v_mov_b64_e32 v[46:47], 0
	v_mov_b64_e32 v[48:49], 0
	v_mov_b64_e32 v[50:51], 0
	v_mov_b64_e32 v[52:53], 0
	v_mov_b64_e32 v[54:55], 0
	v_mov_b64_e32 v[56:57], 0
	v_mov_b64_e32 v[58:59], 0
	v_mov_b64_e32 v[60:61], 0
	v_mov_b64_e32 v[62:63], 0
	v_mov_b64_e32 v[64:65], 0
	v_mov_b64_e32 v[66:67], 0
	v_mov_b64_e32 v[68:69], 0
	v_mov_b64_e32 v[70:71], 0
	v_mov_b64_e32 v[72:73], 0
	v_mov_b64_e32 v[74:75], 0
	v_mov_b64_e32 v[76:77], 0
	v_mov_b64_e32 v[78:79], 0
	v_mov_b64_e32 v[80:81], 0
	v_mov_b64_e32 v[82:83], 0
	v_mov_b64_e32 v[84:85], 0
	v_mov_b64_e32 v[86:87], 0
	v_mov_b64_e32 v[88:89], 0
	v_mov_b64_e32 v[90:91], 0
	v_mov_b64_e32 v[92:93], 0
	v_mov_b64_e32 v[94:95], 0
	v_mov_b64_e32 v[96:97], 0
	v_mov_b64_e32 v[98:99], 0
	v_mov_b64_e32 v[100:101], 0
	v_mov_b64_e32 v[102:103], 0
	v_mov_b64_e32 v[104:105], 0
	v_mov_b64_e32 v[106:107], 0
	v_mov_b64_e32 v[108:109], 0
	v_mov_b64_e32 v[110:111], 0
	v_mov_b64_e32 v[112:113], 0
	v_mov_b64_e32 v[114:115], 0
	v_mov_b64_e32 v[116:117], 0
	v_mov_b64_e32 v[118:119], 0
	v_mov_b64_e32 v[120:121], 0
	v_mov_b64_e32 v[122:123], 0
	v_mov_b64_e32 v[124:125], 0
	v_mov_b64_e32 v[126:127], 0
	v_mov_b64_e32 v[128:129], 0
	s_barrier
	s_branch .LBB0_1358
.LBB0_1357:
	s_mov_b32 s30, s70
	s_mov_b32 s48, s68
	v_mov_b64_e32 v[2:3], 0
	v_mov_b64_e32 v[4:5], 0
	v_mov_b64_e32 v[6:7], 0
	v_mov_b64_e32 v[8:9], 0
	v_mov_b64_e32 v[10:11], 0
	v_mov_b64_e32 v[12:13], 0
	v_mov_b64_e32 v[14:15], 0
	v_mov_b64_e32 v[16:17], 0
	v_mov_b64_e32 v[18:19], 0
	v_mov_b64_e32 v[20:21], 0
	v_mov_b64_e32 v[22:23], 0
	v_mov_b64_e32 v[24:25], 0
	v_mov_b64_e32 v[26:27], 0
	v_mov_b64_e32 v[28:29], 0
	v_mov_b64_e32 v[30:31], 0
	v_mov_b64_e32 v[32:33], 0
	v_mov_b64_e32 v[34:35], 0
	v_mov_b64_e32 v[36:37], 0
	v_mov_b64_e32 v[38:39], 0
	v_mov_b64_e32 v[40:41], 0
	v_mov_b64_e32 v[42:43], 0
	v_mov_b64_e32 v[44:45], 0
	v_mov_b64_e32 v[46:47], 0
	v_mov_b64_e32 v[48:49], 0
	v_mov_b64_e32 v[50:51], 0
	v_mov_b64_e32 v[52:53], 0
	v_mov_b64_e32 v[54:55], 0
	v_mov_b64_e32 v[56:57], 0
	v_mov_b64_e32 v[58:59], 0
	v_mov_b64_e32 v[60:61], 0
	v_mov_b64_e32 v[62:63], 0
	v_mov_b64_e32 v[64:65], 0
	v_mov_b64_e32 v[66:67], 0
	v_mov_b64_e32 v[68:69], 0
	v_mov_b64_e32 v[70:71], 0
	v_mov_b64_e32 v[72:73], 0
	v_mov_b64_e32 v[74:75], 0
	v_mov_b64_e32 v[76:77], 0
	v_mov_b64_e32 v[78:79], 0
	v_mov_b64_e32 v[80:81], 0
	v_mov_b64_e32 v[82:83], 0
	v_mov_b64_e32 v[84:85], 0
	v_mov_b64_e32 v[86:87], 0
	v_mov_b64_e32 v[88:89], 0
	v_mov_b64_e32 v[90:91], 0
	v_mov_b64_e32 v[92:93], 0
	v_mov_b64_e32 v[94:95], 0
	v_mov_b64_e32 v[96:97], 0
	v_mov_b64_e32 v[98:99], 0
	v_mov_b64_e32 v[100:101], 0
	v_mov_b64_e32 v[102:103], 0
	v_mov_b64_e32 v[104:105], 0
	v_mov_b64_e32 v[106:107], 0
	v_mov_b64_e32 v[108:109], 0
	v_mov_b64_e32 v[110:111], 0
	v_mov_b64_e32 v[112:113], 0
	v_mov_b64_e32 v[114:115], 0
	v_mov_b64_e32 v[116:117], 0
	v_mov_b64_e32 v[118:119], 0
	v_mov_b64_e32 v[120:121], 0
	v_mov_b64_e32 v[122:123], 0
	v_mov_b64_e32 v[124:125], 0
	v_mov_b64_e32 v[126:127], 0
	v_mov_b64_e32 v[128:129], 0
	s_mov_b64 s[66:67], s[74:75]
	s_mov_b32 s49, s50
	s_andn2_b64 vcc, exec, s[84:85]
	s_mov_b64 s[36:37], s[72:73]
	s_cbranch_vccz .LBB0_1372

;     DI bool next(int i, Unit& u) const { const long L = (long)i * G + c; if (L >= (long)nM * nN) return false; tile_decode((int)L, nM, nN, u.pm, u.pn); u.z = 0; return true; }
;     DI bool next(int i, Unit& u) const { const long L = (long)i * G + c; if (L >= (long)nZ * nM * nN) return false; const int l = (int)L; u.z = l / (nM * nN); const int r = l % (nM * nN); u.pm = r / nN; u.pn = r % nN; return true; }
;     DI bool next(int i, Unit& u) const { const long L = (long)(i / 3) * G + c; if (L >= (long)nM * nN) return false; tile_decode((int)L, nM, nN, u.pm, u.pn); u.z = i % 3; return true; }
; #define PG8_STAGE(bufoff, gbase, voff) do { _Pragma("unroll") for (int _i = 0; _i < 2; ++_i) \
;         __builtin_amdgcn_global_load_lds((const unsigned*)((const char*)(gbase) + (voff)[_i]), (LAS unsigned*)(lds + (bufoff) + ldsw + _i * 8192), 16, 0, 0); } while (0)
; #define PG8_LDA(dst, b, h) do { _Pragma("unroll") for (int m = 0; m < 4; ++m) _Pragma("unroll") for (int k = 0; k < 2; ++k) dst[m][k] = *(const LAS bf16x8*)(lds + PG8_SA(b, h) + aoff + m * 2048 + k * 1024); } while (0)
; #define PG8_SCHED __builtin_amdgcn_sched_barrier(0)
; template <class Epi, class Sched>
; DI void gemm_phase(LAS unsigned char* lds, const Gemm g, const Sched& S, const Epi& E) {
;     ...
;         const bool has_next = S.next(ui + 1, nxt);
;         const char* nA = has_next ? (const char*)g.A + (size_t)nxt.z * g.zA * 2 + (size_t)nxt.pm * 2 * hstepA : cA;
;         const char* nB = has_next ? (const char*)g.Bt + (size_t)nxt.z * g.zB * 2 + (size_t)nxt.pn * 2 * hstepB : cB;
;         for (int t = 0; t < nt; t += 2) {
;             const bool last = (t == nt - 2);
;             const char* a1 = cA + (size_t)(t + 1) * kstep;
;             const char* a2 = last ? nA : cA + (size_t)(t + 2) * kstep; const char* b2 = last ? nB : cB + (size_t)(t + 2) * kstep;
;             const char* a3 = a2 + kstep; const char* b3 = b2 + kstep;
;             PG8_LDB(B0, 0, 0); PG8_LDB(B1, 0, 1); PG8_SCHED; PG8_LDA(At, 0, 0); PG8_STAGE(PG8_SA(1, 1), a1 + hstepA, voffA);
;     ...
; #pragma unroll
;         for (int a = 0; a < 2; ++a)
; #pragma unroll
;             for (int b = 0; b < 2; ++b)
; #pragma unroll
;                 for (int m = 0; m < 4; ++m)
; #pragma unroll
;                     for (int n = 0; n < 2; ++n) acc[a][b][m][n] = (f32x4){0.f, 0.f, 0.f, 0.f};
;         cur = nxt; cA = nA; cB = nB; ++ui;
.LBB0_1439:
	s_ashr_i32 s73, s72, 31
	s_lshl_b64 s[40:41], s[72:73], 21
	s_add_u32 s74, s12, s40
	s_addc_u32 s75, s13, s41
	s_and_b64 s[40:41], s[92:93], exec
	s_cselect_b32 s28, s75, s39
	s_cselect_b32 s40, s74, s38
	s_ashr_i32 s71, s70, 31
	s_lshl_b64 s[50:51], s[70:71], 21
	s_add_u32 s76, s14, s50
	s_addc_u32 s77, s15, s51
	s_and_b64 s[50:51], s[92:93], exec
	s_cselect_b32 s41, s77, s37
	s_cselect_b32 s45, s76, s36
	s_add_u32 s50, s38, 0x100080
	s_addc_u32 s51, s39, 0
	s_add_u32 s71, s36, 0x100
	s_addc_u32 s73, s37, 0
	s_mov_b32 s87, -2
	v_mov_b64_e32 v[2:3], 0
	v_mov_b64_e32 v[4:5], 0
	v_mov_b64_e32 v[6:7], 0
	v_mov_b64_e32 v[8:9], 0
	v_mov_b64_e32 v[10:11], 0
	v_mov_b64_e32 v[12:13], 0
	v_mov_b64_e32 v[14:15], 0
	v_mov_b64_e32 v[16:17], 0
	v_mov_b64_e32 v[18:19], 0
	v_mov_b64_e32 v[20:21], 0
	v_mov_b64_e32 v[22:23], 0
	v_mov_b64_e32 v[24:25], 0
	v_mov_b64_e32 v[26:27], 0
	v_mov_b64_e32 v[28:29], 0
	v_mov_b64_e32 v[30:31], 0
	v_mov_b64_e32 v[32:33], 0
	v_mov_b64_e32 v[34:35], 0
	v_mov_b64_e32 v[36:37], 0
	v_mov_b64_e32 v[38:39], 0
	v_mov_b64_e32 v[40:41], 0
	v_mov_b64_e32 v[42:43], 0
	v_mov_b64_e32 v[44:45], 0
	v_mov_b64_e32 v[46:47], 0
	v_mov_b64_e32 v[48:49], 0
	v_mov_b64_e32 v[50:51], 0
	v_mov_b64_e32 v[52:53], 0
	v_mov_b64_e32 v[54:55], 0
	v_mov_b64_e32 v[56:57], 0
	v_mov_b64_e32 v[58:59], 0
	v_mov_b64_e32 v[60:61], 0
	v_mov_b64_e32 v[62:63], 0
	v_mov_b64_e32 v[64:65], 0
	v_mov_b64_e32 v[66:67], 0
	v_mov_b64_e32 v[68:69], 0
	v_mov_b64_e32 v[70:71], 0
	v_mov_b64_e32 v[72:73], 0
	v_mov_b64_e32 v[74:75], 0
	v_mov_b64_e32 v[76:77], 0
	v_mov_b64_e32 v[86:87], 0
	v_mov_b64_e32 v[88:89], 0
	v_mov_b64_e32 v[90:91], 0
	v_mov_b64_e32 v[92:93], 0
	v_mov_b64_e32 v[102:103], 0
	v_mov_b64_e32 v[104:105], 0
	v_mov_b64_e32 v[106:107], 0
	v_mov_b64_e32 v[108:109], 0
	v_mov_b64_e32 v[110:111], 0
	v_mov_b64_e32 v[112:113], 0
	v_mov_b64_e32 v[114:115], 0
	v_mov_b64_e32 v[116:117], 0
	v_mov_b64_e32 v[118:119], 0
	v_mov_b64_e32 v[120:121], 0
	v_mov_b64_e32 v[122:123], 0
	v_mov_b64_e32 v[124:125], 0
	v_mov_b64_e32 v[126:127], 0
	v_mov_b64_e32 v[128:129], 0
	v_mov_b64_e32 v[130:131], 0
	v_mov_b64_e32 v[132:133], 0
	v_mov_b64_e32 v[134:135], 0
	v_mov_b64_e32 v[136:137], 0
	v_mov_b64_e32 v[138:139], 0
	v_mov_b64_e32 v[140:141], 0
	v_mov_b64_e32 v[142:143], 0
	v_mov_b64_e32 v[144:145], 0
